# P6 scale epilogue hand-scheduled: rms partial-sum loads in two batches issued up front, counted waits, stores never waited on (on top of the wide epilogues)
# baseline (speedup 1.0000x reference)
; __device__ __forceinline__ unsigned pk2(float lo, float hi) { f32x2 v = {lo, hi}; bf16x2_t b = __builtin_convertvector(v, bf16x2_t); return __builtin_bit_cast(unsigned, b); }
; __device__ __forceinline__ float ss_total(const float* ss, int row) { const f32x4* sp = (const f32x4*)(ss + (size_t)row * 16); const f32x4 a = sp[0], b = sp[1], c = sp[2], d = sp[3];
;     return (((a[0] + a[1]) + (a[2] + a[3])) + ((b[0] + b[1]) + (b[2] + b[3]))) + (((c[0] + c[1]) + (c[2] + c[3])) + ((d[0] + d[1]) + (d[2] + d[3]))); }
;     __device__ __forceinline__ void operator()(const f32x4 (&acc)[2][2][4][2], const pg8::Unit& u, int wr, int wc, int fr, int fq) const {
;         const int row0 = u.pm * 256 + wr * 64 + fr, col0 = u.pn * 256 + wc * 32 + 8 * fq;
; #pragma unroll
;         for (int ai = 0; ai < 2; ++ai)
; #pragma unroll
;             for (int m = 0; m < 4; ++m) { const int row = row0 + ai * 128 + m * 16; const float rs = rsqrtf(ss_total(ss, row) * (1.f / 1024.f) + EPS);
;                 bf16_t* rowp = O + (size_t)row * ldc + col0;
; #pragma unroll
;                 for (int bj = 0; bj < 2; ++bj) { const f32x4 v0 = acc[ai][bj][m][0] * rs, v1 = acc[ai][bj][m][1] * rs;
;                     u32x4 w; w.x = pk2(v0[0], v0[1]); w.y = pk2(v0[2], v0[3]); w.z = pk2(v1[0], v1[1]); w.w = pk2(v1[2], v1[3]);
;                     *(u32x4*)(rowp + bj * 128) = w; } }
.LBB0_983:
	v_lshl_add_u32 v186, s85, 8, v158
	v_lshl_or_b32 v187, s84, 8, v160
	v_lshlrev_b32_e32 v152, 6, v186
	v_mov_b32_e32 v153, 0
	v_lshl_add_u64 v[152:153], s[22:23], 0, v[152:153]
	s_mov_b32 s4, 0x3000
	v_mul_lo_u32 v164, v186, s4
	v_lshl_add_u32 v164, v187, 1, v164
	v_mov_b32_e32 v165, 0
	v_lshl_add_u64 v[154:155], s[14:15], 0, v[164:165]
	global_load_dwordx4 v[164:167], v[152:153], off
	global_load_dwordx4 v[168:171], v[152:153], off offset:16
	global_load_dwordx4 v[172:175], v[152:153], off offset:32
	global_load_dwordx4 v[176:179], v[152:153], off offset:48
	s_mov_b64 s[4:5], 0x400
	v_lshl_add_u64 v[152:153], v[152:153], 0, s[4:5]
	global_load_dwordx4 v[180:183], v[152:153], off
	global_load_dwordx4 v[184:187], v[152:153], off offset:16
	global_load_dwordx4 v[204:207], v[152:153], off offset:32
	global_load_dwordx4 v[208:211], v[152:153], off offset:48
	s_mov_b64 s[4:5], 0x400
	v_lshl_add_u64 v[152:153], v[152:153], 0, s[4:5]
	global_load_dwordx4 v[212:215], v[152:153], off
	global_load_dwordx4 v[216:219], v[152:153], off offset:16
	global_load_dwordx4 v[220:223], v[152:153], off offset:32
	global_load_dwordx4 v[224:227], v[152:153], off offset:48
	s_mov_b64 s[4:5], 0x400
	v_lshl_add_u64 v[152:153], v[152:153], 0, s[4:5]
	global_load_dwordx4 v[228:231], v[152:153], off
	global_load_dwordx4 v[232:235], v[152:153], off offset:16
	global_load_dwordx4 v[236:239], v[152:153], off offset:32
	global_load_dwordx4 v[240:243], v[152:153], off offset:48
	s_mov_b64 s[4:5], 0x1400
	v_lshl_add_u64 v[152:153], v[152:153], 0, s[4:5]
	s_waitcnt vmcnt(0)
	v_add_f32_e32 v164, v164, v165
	v_add_f32_e32 v168, v168, v169
	v_add_f32_e32 v172, v172, v173
	v_add_f32_e32 v176, v176, v177
	v_add_f32_e32 v166, v166, v167
	v_add_f32_e32 v170, v170, v171
	v_add_f32_e32 v174, v174, v175
	v_add_f32_e32 v178, v178, v179
	v_add_f32_e32 v164, v164, v166
	v_add_f32_e32 v168, v168, v170
	v_add_f32_e32 v172, v172, v174
	v_add_f32_e32 v176, v176, v178
	v_add_f32_e32 v164, v164, v168
	v_add_f32_e32 v172, v172, v176
	v_add_f32_e32 v164, v164, v172
	v_fmamk_f32 v164, v164, 0x3a800000, v190
	v_cmp_gt_f32_e32 vcc, s66, v164
	v_mul_f32_e32 v244, 0x4b800000, v164
	s_nop 1
	v_cndmask_b32_e32 v164, v164, v244, vcc
	v_rsq_f32_e32 v164, v164
	s_nop 0
	v_mul_f32_e32 v244, 0x45800000, v164
	v_cndmask_b32_e32 v156, v164, v244, vcc
	v_add_f32_e32 v180, v180, v181
	v_add_f32_e32 v184, v184, v185
	v_add_f32_e32 v204, v204, v205
	v_add_f32_e32 v208, v208, v209
	v_add_f32_e32 v182, v182, v183
	v_add_f32_e32 v186, v186, v187
	v_add_f32_e32 v206, v206, v207
	v_add_f32_e32 v210, v210, v211
	v_add_f32_e32 v180, v180, v182
	v_add_f32_e32 v184, v184, v186
	v_add_f32_e32 v204, v204, v206
	v_add_f32_e32 v208, v208, v210
	v_add_f32_e32 v180, v180, v184
	v_add_f32_e32 v204, v204, v208
	v_add_f32_e32 v180, v180, v204
	v_fmamk_f32 v180, v180, 0x3a800000, v190
	v_cmp_gt_f32_e32 vcc, s66, v180
	v_mul_f32_e32 v244, 0x4b800000, v180
	s_nop 1
	v_cndmask_b32_e32 v180, v180, v244, vcc
	v_rsq_f32_e32 v180, v180
	s_nop 0
	v_mul_f32_e32 v244, 0x45800000, v180
	v_cndmask_b32_e32 v157, v180, v244, vcc
	v_add_f32_e32 v212, v212, v213
	v_add_f32_e32 v216, v216, v217
	v_add_f32_e32 v220, v220, v221
	v_add_f32_e32 v224, v224, v225
	v_add_f32_e32 v214, v214, v215
	v_add_f32_e32 v218, v218, v219
	v_add_f32_e32 v222, v222, v223
	v_add_f32_e32 v226, v226, v227
	v_add_f32_e32 v212, v212, v214
	v_add_f32_e32 v216, v216, v218
	v_add_f32_e32 v220, v220, v222
	v_add_f32_e32 v224, v224, v226
	v_add_f32_e32 v212, v212, v216
	v_add_f32_e32 v220, v220, v224
	v_add_f32_e32 v212, v212, v220
	v_fmamk_f32 v212, v212, 0x3a800000, v190
	v_cmp_gt_f32_e32 vcc, s66, v212
	v_mul_f32_e32 v244, 0x4b800000, v212
	s_nop 1
	v_cndmask_b32_e32 v212, v212, v244, vcc
	v_rsq_f32_e32 v212, v212
	s_nop 0
	v_mul_f32_e32 v244, 0x45800000, v212
	v_cndmask_b32_e32 v162, v212, v244, vcc
	v_add_f32_e32 v228, v228, v229
	v_add_f32_e32 v232, v232, v233
	v_add_f32_e32 v236, v236, v237
	v_add_f32_e32 v240, v240, v241
	v_add_f32_e32 v230, v230, v231
	v_add_f32_e32 v234, v234, v235
	v_add_f32_e32 v238, v238, v239
	v_add_f32_e32 v242, v242, v243
	v_add_f32_e32 v228, v228, v230
	v_add_f32_e32 v232, v232, v234
	v_add_f32_e32 v236, v236, v238
	v_add_f32_e32 v240, v240, v242
	v_add_f32_e32 v228, v228, v232
	v_add_f32_e32 v236, v236, v240
	v_add_f32_e32 v228, v228, v236
	v_fmamk_f32 v228, v228, 0x3a800000, v190
	v_cmp_gt_f32_e32 vcc, s66, v228
	v_mul_f32_e32 v244, 0x4b800000, v228
	s_nop 1
	v_cndmask_b32_e32 v228, v228, v244, vcc
	v_rsq_f32_e32 v228, v228
	s_nop 0
	v_mul_f32_e32 v244, 0x45800000, v228
	v_cndmask_b32_e32 v163, v228, v244, vcc
	global_load_dwordx4 v[164:167], v[152:153], off
	global_load_dwordx4 v[168:171], v[152:153], off offset:16
	global_load_dwordx4 v[172:175], v[152:153], off offset:32
	global_load_dwordx4 v[176:179], v[152:153], off offset:48
	s_mov_b64 s[4:5], 0x400
	v_lshl_add_u64 v[152:153], v[152:153], 0, s[4:5]
	global_load_dwordx4 v[180:183], v[152:153], off
	global_load_dwordx4 v[184:187], v[152:153], off offset:16
	global_load_dwordx4 v[204:207], v[152:153], off offset:32
	global_load_dwordx4 v[208:211], v[152:153], off offset:48
	s_mov_b64 s[4:5], 0x400
	v_lshl_add_u64 v[152:153], v[152:153], 0, s[4:5]
	global_load_dwordx4 v[212:215], v[152:153], off
	global_load_dwordx4 v[216:219], v[152:153], off offset:16
	global_load_dwordx4 v[220:223], v[152:153], off offset:32
	global_load_dwordx4 v[224:227], v[152:153], off offset:48
	s_mov_b64 s[4:5], 0x400
	v_lshl_add_u64 v[152:153], v[152:153], 0, s[4:5]
	global_load_dwordx4 v[228:231], v[152:153], off
	global_load_dwordx4 v[232:235], v[152:153], off offset:16
; __device__ __forceinline__ unsigned pk2(float lo, float hi) { f32x2 v = {lo, hi}; bf16x2_t b = __builtin_convertvector(v, bf16x2_t); return __builtin_bit_cast(unsigned, b); }
;     __device__ __forceinline__ void operator()(const f32x4 (&acc)[2][2][4][2], const pg8::Unit& u, int wr, int wc, int fr, int fq) const {
;         const int row0 = u.pm * 256 + wr * 64 + fr, col0 = u.pn * 256 + wc * 32 + 8 * fq;
; #pragma unroll
;         for (int ai = 0; ai < 2; ++ai)
; #pragma unroll
;             for (int m = 0; m < 4; ++m) { const int row = row0 + ai * 128 + m * 16; const float rs = rsqrtf(ss_total(ss, row) * (1.f / 1024.f) + EPS);
;                 bf16_t* rowp = O + (size_t)row * ldc + col0;
; #pragma unroll
;                 for (int bj = 0; bj < 2; ++bj) { const f32x4 v0 = acc[ai][bj][m][0] * rs, v1 = acc[ai][bj][m][1] * rs;
;                     u32x4 w; w.x = pk2(v0[0], v0[1]); w.y = pk2(v0[2], v0[3]); w.z = pk2(v1[0], v1[1]); w.w = pk2(v1[2], v1[3]);
;                     *(u32x4*)(rowp + bj * 128) = w; } }
;     }
	global_load_dwordx4 v[236:239], v[152:153], off offset:32
	global_load_dwordx4 v[240:243], v[152:153], off offset:48
	v_mul_f32_e32 v126, v126, v156
	v_mul_f32_e32 v127, v127, v156
	v_mul_f32_e32 v128, v128, v156
	v_mul_f32_e32 v129, v129, v156
	v_mul_f32_e32 v122, v122, v156
	v_mul_f32_e32 v123, v123, v156
	v_mul_f32_e32 v124, v124, v156
	v_mul_f32_e32 v125, v125, v156
	v_cvt_pk_bf16_f32 v126, v126, v127
	v_cvt_pk_bf16_f32 v127, v128, v129
	v_cvt_pk_bf16_f32 v128, v122, v123
	v_cvt_pk_bf16_f32 v129, v124, v125
	global_store_dwordx4 v[154:155], v[126:129], off
	v_mul_f32_e32 v118, v118, v156
	v_mul_f32_e32 v119, v119, v156
	v_mul_f32_e32 v120, v120, v156
	v_mul_f32_e32 v121, v121, v156
	v_mul_f32_e32 v114, v114, v156
	v_mul_f32_e32 v115, v115, v156
	v_mul_f32_e32 v116, v116, v156
	v_mul_f32_e32 v117, v117, v156
	v_cvt_pk_bf16_f32 v118, v118, v119
	v_cvt_pk_bf16_f32 v119, v120, v121
	v_cvt_pk_bf16_f32 v120, v114, v115
	v_cvt_pk_bf16_f32 v121, v116, v117
	global_store_dwordx4 v[154:155], v[118:121], off offset:256
	s_mov_b64 s[4:5], 0x30000
	v_lshl_add_u64 v[154:155], v[154:155], 0, s[4:5]
	v_mul_f32_e32 v110, v110, v157
	v_mul_f32_e32 v111, v111, v157
	v_mul_f32_e32 v112, v112, v157
	v_mul_f32_e32 v113, v113, v157
	v_mul_f32_e32 v106, v106, v157
	v_mul_f32_e32 v107, v107, v157
	v_mul_f32_e32 v108, v108, v157
	v_mul_f32_e32 v109, v109, v157
	v_cvt_pk_bf16_f32 v110, v110, v111
	v_cvt_pk_bf16_f32 v111, v112, v113
	v_cvt_pk_bf16_f32 v112, v106, v107
	v_cvt_pk_bf16_f32 v113, v108, v109
	global_store_dwordx4 v[154:155], v[110:113], off
	v_mul_f32_e32 v102, v102, v157
	v_mul_f32_e32 v103, v103, v157
	v_mul_f32_e32 v104, v104, v157
	v_mul_f32_e32 v105, v105, v157
	v_mul_f32_e32 v98, v98, v157
	v_mul_f32_e32 v99, v99, v157
	v_mul_f32_e32 v100, v100, v157
	v_mul_f32_e32 v101, v101, v157
	v_cvt_pk_bf16_f32 v102, v102, v103
	v_cvt_pk_bf16_f32 v103, v104, v105
	v_cvt_pk_bf16_f32 v104, v98, v99
	v_cvt_pk_bf16_f32 v105, v100, v101
	global_store_dwordx4 v[154:155], v[102:105], off offset:256
	s_mov_b64 s[4:5], 0x30000
	v_lshl_add_u64 v[154:155], v[154:155], 0, s[4:5]
	v_mul_f32_e32 v94, v94, v162
	v_mul_f32_e32 v95, v95, v162
	v_mul_f32_e32 v96, v96, v162
	v_mul_f32_e32 v97, v97, v162
	v_mul_f32_e32 v90, v90, v162
	v_mul_f32_e32 v91, v91, v162
	v_mul_f32_e32 v92, v92, v162
	v_mul_f32_e32 v93, v93, v162
	v_cvt_pk_bf16_f32 v94, v94, v95
	v_cvt_pk_bf16_f32 v95, v96, v97
	v_cvt_pk_bf16_f32 v96, v90, v91
	v_cvt_pk_bf16_f32 v97, v92, v93
	global_store_dwordx4 v[154:155], v[94:97], off
	v_mul_f32_e32 v86, v86, v162
	v_mul_f32_e32 v87, v87, v162
	v_mul_f32_e32 v88, v88, v162
	v_mul_f32_e32 v89, v89, v162
	v_mul_f32_e32 v82, v82, v162
	v_mul_f32_e32 v83, v83, v162
	v_mul_f32_e32 v84, v84, v162
	v_mul_f32_e32 v85, v85, v162
	v_cvt_pk_bf16_f32 v86, v86, v87
	v_cvt_pk_bf16_f32 v87, v88, v89
	v_cvt_pk_bf16_f32 v88, v82, v83
	v_cvt_pk_bf16_f32 v89, v84, v85
	global_store_dwordx4 v[154:155], v[86:89], off offset:256
	s_mov_b64 s[4:5], 0x30000
	v_lshl_add_u64 v[154:155], v[154:155], 0, s[4:5]
	v_mul_f32_e32 v78, v78, v163
	v_mul_f32_e32 v79, v79, v163
	v_mul_f32_e32 v80, v80, v163
	v_mul_f32_e32 v81, v81, v163
	v_mul_f32_e32 v74, v74, v163
	v_mul_f32_e32 v75, v75, v163
	v_mul_f32_e32 v76, v76, v163
	v_mul_f32_e32 v77, v77, v163
	v_cvt_pk_bf16_f32 v78, v78, v79
	v_cvt_pk_bf16_f32 v79, v80, v81
	v_cvt_pk_bf16_f32 v80, v74, v75
	v_cvt_pk_bf16_f32 v81, v76, v77
	global_store_dwordx4 v[154:155], v[78:81], off
	v_mul_f32_e32 v70, v70, v163
	v_mul_f32_e32 v71, v71, v163
	v_mul_f32_e32 v72, v72, v163
	v_mul_f32_e32 v73, v73, v163
	v_mul_f32_e32 v66, v66, v163
	v_mul_f32_e32 v67, v67, v163
	v_mul_f32_e32 v68, v68, v163
	v_mul_f32_e32 v69, v69, v163
	v_cvt_pk_bf16_f32 v70, v70, v71
	v_cvt_pk_bf16_f32 v71, v72, v73
	v_cvt_pk_bf16_f32 v72, v66, v67
	v_cvt_pk_bf16_f32 v73, v68, v69
	global_store_dwordx4 v[154:155], v[70:73], off offset:256
	s_mov_b64 s[4:5], 0xf0000
	v_lshl_add_u64 v[154:155], v[154:155], 0, s[4:5]
	s_waitcnt vmcnt(8)
; __device__ __forceinline__ unsigned pk2(float lo, float hi) { f32x2 v = {lo, hi}; bf16x2_t b = __builtin_convertvector(v, bf16x2_t); return __builtin_bit_cast(unsigned, b); }
; __device__ __forceinline__ float ss_total(const float* ss, int row) { const f32x4* sp = (const f32x4*)(ss + (size_t)row * 16); const f32x4 a = sp[0], b = sp[1], c = sp[2], d = sp[3];
;     return (((a[0] + a[1]) + (a[2] + a[3])) + ((b[0] + b[1]) + (b[2] + b[3]))) + (((c[0] + c[1]) + (c[2] + c[3])) + ((d[0] + d[1]) + (d[2] + d[3]))); }
;     __device__ __forceinline__ void operator()(const f32x4 (&acc)[2][2][4][2], const pg8::Unit& u, int wr, int wc, int fr, int fq) const {
;         const int row0 = u.pm * 256 + wr * 64 + fr, col0 = u.pn * 256 + wc * 32 + 8 * fq;
; #pragma unroll
;         for (int ai = 0; ai < 2; ++ai)
; #pragma unroll
;             for (int m = 0; m < 4; ++m) { const int row = row0 + ai * 128 + m * 16; const float rs = rsqrtf(ss_total(ss, row) * (1.f / 1024.f) + EPS);
;                 bf16_t* rowp = O + (size_t)row * ldc + col0;
; #pragma unroll
;                 for (int bj = 0; bj < 2; ++bj) { const f32x4 v0 = acc[ai][bj][m][0] * rs, v1 = acc[ai][bj][m][1] * rs;
;                     u32x4 w; w.x = pk2(v0[0], v0[1]); w.y = pk2(v0[2], v0[3]); w.z = pk2(v1[0], v1[1]); w.w = pk2(v1[2], v1[3]);
;                     *(u32x4*)(rowp + bj * 128) = w; } }
;     }
	v_add_f32_e32 v164, v164, v165
	v_add_f32_e32 v168, v168, v169
	v_add_f32_e32 v172, v172, v173
	v_add_f32_e32 v176, v176, v177
	v_add_f32_e32 v166, v166, v167
	v_add_f32_e32 v170, v170, v171
	v_add_f32_e32 v174, v174, v175
	v_add_f32_e32 v178, v178, v179
	v_add_f32_e32 v164, v164, v166
	v_add_f32_e32 v168, v168, v170
	v_add_f32_e32 v172, v172, v174
	v_add_f32_e32 v176, v176, v178
	v_add_f32_e32 v164, v164, v168
	v_add_f32_e32 v172, v172, v176
	v_add_f32_e32 v164, v164, v172
	v_fmamk_f32 v164, v164, 0x3a800000, v190
	v_cmp_gt_f32_e32 vcc, s66, v164
	v_mul_f32_e32 v244, 0x4b800000, v164
	s_nop 1
	v_cndmask_b32_e32 v164, v164, v244, vcc
	v_rsq_f32_e32 v164, v164
	s_nop 0
	v_mul_f32_e32 v244, 0x45800000, v164
	v_cndmask_b32_e32 v156, v164, v244, vcc
	v_add_f32_e32 v180, v180, v181
	v_add_f32_e32 v184, v184, v185
	v_add_f32_e32 v204, v204, v205
	v_add_f32_e32 v208, v208, v209
	v_add_f32_e32 v182, v182, v183
	v_add_f32_e32 v186, v186, v187
	v_add_f32_e32 v206, v206, v207
	v_add_f32_e32 v210, v210, v211
	v_add_f32_e32 v180, v180, v182
	v_add_f32_e32 v184, v184, v186
	v_add_f32_e32 v204, v204, v206
	v_add_f32_e32 v208, v208, v210
	v_add_f32_e32 v180, v180, v184
	v_add_f32_e32 v204, v204, v208
	v_add_f32_e32 v180, v180, v204
	v_fmamk_f32 v180, v180, 0x3a800000, v190
	v_cmp_gt_f32_e32 vcc, s66, v180
	v_mul_f32_e32 v244, 0x4b800000, v180
	s_nop 1
	v_cndmask_b32_e32 v180, v180, v244, vcc
	v_rsq_f32_e32 v180, v180
	s_nop 0
	v_mul_f32_e32 v244, 0x45800000, v180
	v_cndmask_b32_e32 v157, v180, v244, vcc
	v_add_f32_e32 v212, v212, v213
	v_add_f32_e32 v216, v216, v217
	v_add_f32_e32 v220, v220, v221
	v_add_f32_e32 v224, v224, v225
	v_add_f32_e32 v214, v214, v215
	v_add_f32_e32 v218, v218, v219
	v_add_f32_e32 v222, v222, v223
	v_add_f32_e32 v226, v226, v227
	v_add_f32_e32 v212, v212, v214
	v_add_f32_e32 v216, v216, v218
	v_add_f32_e32 v220, v220, v222
	v_add_f32_e32 v224, v224, v226
	v_add_f32_e32 v212, v212, v216
	v_add_f32_e32 v220, v220, v224
	v_add_f32_e32 v212, v212, v220
	v_fmamk_f32 v212, v212, 0x3a800000, v190
	v_cmp_gt_f32_e32 vcc, s66, v212
	v_mul_f32_e32 v244, 0x4b800000, v212
	s_nop 1
	v_cndmask_b32_e32 v212, v212, v244, vcc
	v_rsq_f32_e32 v212, v212
	s_nop 0
	v_mul_f32_e32 v244, 0x45800000, v212
	v_cndmask_b32_e32 v162, v212, v244, vcc
	v_add_f32_e32 v228, v228, v229
	v_add_f32_e32 v232, v232, v233
	v_add_f32_e32 v236, v236, v237
	v_add_f32_e32 v240, v240, v241
	v_add_f32_e32 v230, v230, v231
	v_add_f32_e32 v234, v234, v235
	v_add_f32_e32 v238, v238, v239
	v_add_f32_e32 v242, v242, v243
	v_add_f32_e32 v228, v228, v230
	v_add_f32_e32 v232, v232, v234
	v_add_f32_e32 v236, v236, v238
	v_add_f32_e32 v240, v240, v242
	v_add_f32_e32 v228, v228, v232
	v_add_f32_e32 v236, v236, v240
	v_add_f32_e32 v228, v228, v236
	v_fmamk_f32 v228, v228, 0x3a800000, v190
	v_cmp_gt_f32_e32 vcc, s66, v228
	v_mul_f32_e32 v244, 0x4b800000, v228
	s_nop 1
	v_cndmask_b32_e32 v228, v228, v244, vcc
	v_rsq_f32_e32 v228, v228
	s_nop 0
	v_mul_f32_e32 v244, 0x45800000, v228
	v_cndmask_b32_e32 v163, v228, v244, vcc
	v_mul_f32_e32 v62, v62, v156
	v_mul_f32_e32 v63, v63, v156
	v_mul_f32_e32 v64, v64, v156
	v_mul_f32_e32 v65, v65, v156
	v_mul_f32_e32 v58, v58, v156
	v_mul_f32_e32 v59, v59, v156
	v_mul_f32_e32 v60, v60, v156
	v_mul_f32_e32 v61, v61, v156
	v_cvt_pk_bf16_f32 v62, v62, v63
	v_cvt_pk_bf16_f32 v63, v64, v65
	v_cvt_pk_bf16_f32 v64, v58, v59
	v_cvt_pk_bf16_f32 v65, v60, v61
	global_store_dwordx4 v[154:155], v[62:65], off
	v_mul_f32_e32 v54, v54, v156
	v_mul_f32_e32 v55, v55, v156
	v_mul_f32_e32 v56, v56, v156
	v_mul_f32_e32 v57, v57, v156
	v_mul_f32_e32 v50, v50, v156
	v_mul_f32_e32 v51, v51, v156
	v_mul_f32_e32 v52, v52, v156
	v_mul_f32_e32 v53, v53, v156
	v_cvt_pk_bf16_f32 v54, v54, v55
	v_cvt_pk_bf16_f32 v55, v56, v57
	v_cvt_pk_bf16_f32 v56, v50, v51
	v_cvt_pk_bf16_f32 v57, v52, v53
	global_store_dwordx4 v[154:155], v[54:57], off offset:256
	s_mov_b64 s[4:5], 0x30000
	v_lshl_add_u64 v[154:155], v[154:155], 0, s[4:5]
	v_mul_f32_e32 v46, v46, v157
	v_mul_f32_e32 v47, v47, v157
	v_mul_f32_e32 v48, v48, v157
	v_mul_f32_e32 v49, v49, v157
	v_mul_f32_e32 v42, v42, v157
	v_mul_f32_e32 v43, v43, v157
	v_mul_f32_e32 v44, v44, v157
	v_mul_f32_e32 v45, v45, v157
	v_cvt_pk_bf16_f32 v46, v46, v47
	v_cvt_pk_bf16_f32 v47, v48, v49
	v_cvt_pk_bf16_f32 v48, v42, v43
	v_cvt_pk_bf16_f32 v49, v44, v45
	global_store_dwordx4 v[154:155], v[46:49], off
	v_mul_f32_e32 v38, v38, v157
	v_mul_f32_e32 v39, v39, v157
	v_mul_f32_e32 v40, v40, v157
	v_mul_f32_e32 v41, v41, v157
	v_mul_f32_e32 v34, v34, v157
	v_mul_f32_e32 v35, v35, v157
	v_mul_f32_e32 v36, v36, v157
	v_mul_f32_e32 v37, v37, v157
	v_cvt_pk_bf16_f32 v38, v38, v39
	v_cvt_pk_bf16_f32 v39, v40, v41
	v_cvt_pk_bf16_f32 v40, v34, v35
	v_cvt_pk_bf16_f32 v41, v36, v37
	global_store_dwordx4 v[154:155], v[38:41], off offset:256
	s_mov_b64 s[4:5], 0x30000
	v_lshl_add_u64 v[154:155], v[154:155], 0, s[4:5]
	v_mul_f32_e32 v30, v30, v162
	v_mul_f32_e32 v31, v31, v162
	v_mul_f32_e32 v32, v32, v162
	v_mul_f32_e32 v33, v33, v162
	v_mul_f32_e32 v26, v26, v162
	v_mul_f32_e32 v27, v27, v162
	v_mul_f32_e32 v28, v28, v162
	v_mul_f32_e32 v29, v29, v162
	v_cvt_pk_bf16_f32 v30, v30, v31
	v_cvt_pk_bf16_f32 v31, v32, v33
	v_cvt_pk_bf16_f32 v32, v26, v27
	v_cvt_pk_bf16_f32 v33, v28, v29
	global_store_dwordx4 v[154:155], v[30:33], off
	v_mul_f32_e32 v22, v22, v162
	v_mul_f32_e32 v23, v23, v162
	v_mul_f32_e32 v24, v24, v162
	v_mul_f32_e32 v25, v25, v162
	v_mul_f32_e32 v18, v18, v162
	v_mul_f32_e32 v19, v19, v162
	v_mul_f32_e32 v20, v20, v162
	v_mul_f32_e32 v21, v21, v162
	v_cvt_pk_bf16_f32 v22, v22, v23
	v_cvt_pk_bf16_f32 v23, v24, v25
	v_cvt_pk_bf16_f32 v24, v18, v19
	v_cvt_pk_bf16_f32 v25, v20, v21
	global_store_dwordx4 v[154:155], v[22:25], off offset:256
	s_mov_b64 s[4:5], 0x30000
	v_lshl_add_u64 v[154:155], v[154:155], 0, s[4:5]
	v_mul_f32_e32 v14, v14, v163
	v_mul_f32_e32 v15, v15, v163
	v_mul_f32_e32 v16, v16, v163
	v_mul_f32_e32 v17, v17, v163
	v_mul_f32_e32 v10, v10, v163
	v_mul_f32_e32 v11, v11, v163
	v_mul_f32_e32 v12, v12, v163
	v_mul_f32_e32 v13, v13, v163
	v_cvt_pk_bf16_f32 v14, v14, v15
	v_cvt_pk_bf16_f32 v15, v16, v17
	v_cvt_pk_bf16_f32 v16, v10, v11
	v_cvt_pk_bf16_f32 v17, v12, v13
	global_store_dwordx4 v[154:155], v[14:17], off
	v_mul_f32_e32 v6, v6, v163
	v_mul_f32_e32 v7, v7, v163
	v_mul_f32_e32 v8, v8, v163
	v_mul_f32_e32 v9, v9, v163
	v_mul_f32_e32 v2, v2, v163
	v_mul_f32_e32 v3, v3, v163
	v_mul_f32_e32 v4, v4, v163
	v_mul_f32_e32 v5, v5, v163
	v_cvt_pk_bf16_f32 v6, v6, v7
	v_cvt_pk_bf16_f32 v7, v8, v9
	v_cvt_pk_bf16_f32 v8, v2, v3
	v_cvt_pk_bf16_f32 v9, v4, v5
	global_store_dwordx4 v[154:155], v[6:9], off offset:256
	s_mov_b64 s[4:5], -1
	s_andn2_b64 vcc, exec, s[38:39]
	s_cbranch_vccnz .LBB0_976
	s_andn2_b64 vcc, exec, s[0:1]
	s_cbranch_vccnz .LBB0_975
	s_barrier
	s_branch .LBB0_975
